# diff-attn steady loop: softmax row sums via 4 ones-operand MFMAs per tile instead of 34 VALU adds
# speedup vs baseline: 1.0215x; 1.0019x over previous
; template <int NMAP, int VD, bool SWA> ...
;     ...
;     { const bf16_t* qr = Qp + (size_t)(16 * w + fr) * qpitch + fq * 8;
; #pragma unroll
;       for (int mp = 0; mp < NMAP; ++mp)
; #pragma unroll
;           for (int ks = 0; ks < 2; ++ks) qf[mp][ks] = *(const bf16x8*)(qr + mp * 64 + ks * 32); }
;     f32x4 oacc[NMAP][NET], negm[NMAP]; float mrun[NMAP], lsum[NMAP];
; #pragma unroll
;     for (int mp = 0; mp < NMAP; ++mp) { mrun[mp] = 0.f; lsum[mp] = 0.f; negm[mp] = (f32x4){0.f, 0.f, 0.f, 0.f};
; #pragma unroll
;         for (int et = 0; et < NET; ++et) oacc[mp][et] = (f32x4){0.f, 0.f, 0.f, 0.f}; }
;     const int ntiles = n0 + (t1hi - t1lo);
;     u32x4 kreg[NKC], vreg[NVC];
;     ...
;     ATT_LOAD(ATT_TILE(0));
;     ATT_STORE(0);
;     if (ntiles > 1) ATT_LOAD(ATT_TILE(1));
;     __syncthreads();
; __device__ __forceinline__ void mix_phase(const Args& a, LAS unsigned char* lds, int l, int tid_in, int G) {
;     ...
;         if (u < e3) {
;             const bool is_swa = (u >= e0 && u < e1) || (u >= e2);
;             const bool is_ctx = (u >= e1);
;             int b, hh, qb, row0;
;             if (u < e0) {
;                 const int v = u, x = v & 7, slot = (v >> 3) & 31, rnd = v >> 8, P = x * 4 + rnd * 2 + (slot >> 4);
;                 b = P >> 2; hh = P & 3; qb = slot & 15; row0 = b * SEQ + 128 * qb; }
;             else if (u < e1) { const int v = u - e0, x = v & 7, slot = (v >> 3) & 31, P = x * 2 + (slot >> 4); b = P >> 1; hh = P & 1; qb = slot & 15; row0 = b * SEQ + 128 * qb; }
;             else if (u < e2) { const int v = u - e1; b = v >> 3; hh = (v >> 1) & 3; qb = v & 1; row0 = T_LAT + b * CTXL + 128 * qb; }
;             else { const int v = u - e2; b = v >> 2; hh = (v >> 1) & 1; qb = v & 1; row0 = T_LAT + b * CTXL + 128 * qb; }
;             if (!is_swa) {
;                 attn_unit<2, 128, false>(lds, QB + (size_t)row0 * 512 + hh * 128, 512, KB + (size_t)(b * 4 + hh) * NKEY * 128, VBt + (size_t)(b * 4 + hh) * NKEY * 128,
;                                          is_ctx ? 4 : 36, 0, 0, 0, 0.f, lam, gsub, post_scale, O + (size_t)row0 * DM + 256 + hh * 128, tid);
.LBB0_121:
	s_and_b32 s0, s22, 0xffffff00
	s_cmpk_eq_i32 s0, 0x200
	s_cselect_b64 s[0:1], -1, 0
	s_cmp_ge_i32 s22, s13
	s_cselect_b64 s[8:9], -1, 0
	s_or_b64 s[10:11], s[8:9], s[0:1]
	s_cmpk_gt_i32 s22, 0x2ff
	s_mov_b64 s[8:9], -1
	s_cselect_b64 s[0:1], -1, 0
	s_and_b64 vcc, exec, s[10:11]
	v_ashrrev_i32_e32 v178, 31, v176
	v_lshlrev_b32_e32 v175, 2, v177
	s_cbranch_vccnz .LBB0_139
	s_ashr_i32 s21, s20, 31
	s_lshl_b64 s[8:9], s[20:21], 10
	v_readlane_b32 s3, v252, 43
	s_add_u32 s3, s3, s8
	v_readlane_b32 s8, v252, 44
	s_addc_u32 s8, s8, s9
	s_lshl_b32 s25, s16, 7
	s_lshl_b32 s9, s16, 8
	s_waitcnt vmcnt(0) lgkmcnt(0)
	v_add_u32_e32 v22, 0x200, v176
	s_add_u32 s28, s3, s9
	v_lshrrev_b32_e32 v0, 28, v178
	v_ashrrev_i32_e32 v23, 31, v22
	s_addc_u32 s29, s8, 0
	s_lshl_b32 s14, s24, 2
	v_add_u32_e32 v0, v176, v0
	v_lshrrev_b32_e32 v23, 28, v23
	s_add_i32 s14, s14, s16
	v_ashrrev_i32_e32 v34, 4, v0
	v_add_u32_e32 v23, v22, v23
	s_mul_i32 s8, s14, 0x90000
	v_readlane_b32 s9, v252, 47
	v_and_b32_e32 v0, -16, v0
	v_ashrrev_i32_e32 v35, 31, v34
	v_ashrrev_i32_e32 v36, 4, v23
	v_and_b32_e32 v23, -16, v23
	s_mul_hi_i32 s3, s14, 0x90000
	s_add_u32 s10, s9, s8
	v_readlane_b32 s9, v252, 48
	v_sub_u32_e32 v0, v176, v0
	v_lshlrev_b64 v[58:59], 8, v[34:35]
	v_sub_u32_e32 v35, v22, v23
	s_addc_u32 s11, s9, s3
	v_readlane_b32 s9, v252, 49
	v_ashrrev_i32_e32 v161, 31, v160
	v_lshlrev_b32_e32 v20, 3, v0
	v_ashrrev_i32_e32 v37, 31, v36
	v_lshlrev_b32_e32 v24, 3, v35
	s_add_u32 s8, s9, s8
	v_readlane_b32 s9, v252, 50
	v_lshlrev_b64 v[2:3], 10, v[160:161]
	v_ashrrev_i32_e32 v21, 31, v20
	v_lshlrev_b64 v[94:95], 8, v[36:37]
	v_ashrrev_i32_e32 v25, 31, v24
	s_addc_u32 s9, s9, s3
	v_lshl_add_u64 v[2:3], s[28:29], 0, v[2:3]
	v_mov_b32_e32 v163, v1
	v_lshl_add_u64 v[18:19], s[10:11], 0, v[58:59]
	v_lshlrev_b64 v[60:61], 1, v[20:21]
	v_lshl_add_u64 v[22:23], s[10:11], 0, v[94:95]
	v_lshlrev_b64 v[96:97], 1, v[24:25]
	v_lshl_add_u64 v[2:3], v[2:3], 0, v[162:163]
	v_lshl_add_u64 v[18:19], v[18:19], 0, v[60:61]
	v_lshl_add_u64 v[22:23], v[22:23], 0, v[96:97]
	v_lshl_add_u64 v[26:27], s[8:9], 0, v[58:59]
	global_load_dwordx4 v[14:17], v[2:3], off
	global_load_dwordx4 v[10:13], v[2:3], off offset:64
	global_load_dwordx4 v[6:9], v[2:3], off offset:128
	s_nop 0
	global_load_dwordx4 v[2:5], v[2:3], off offset:192
	v_lshl_add_u64 v[26:27], v[26:27], 0, v[60:61]
	global_load_dwordx4 v[18:21], v[18:19], off
	v_lshl_add_u64 v[30:31], s[8:9], 0, v[94:95]
	global_load_dwordx4 v[22:25], v[22:23], off
	v_lshl_add_u64 v[30:31], v[30:31], 0, v[96:97]
	global_load_dwordx4 v[26:29], v[26:27], off
	s_movk_i32 s15, 0x120
	global_load_dwordx4 v[30:33], v[30:31], off
	v_mul_lo_u32 v208, v34, s15
	v_lshlrev_b32_e32 v209, 4, v0
	v_mul_lo_u32 v210, v36, s15
	v_lshlrev_b32_e32 v211, 4, v35
	v_add3_u32 v34, 0, v208, v209
	v_add3_u32 v35, 0, v210, v211
	s_mov_b64 s[34:35], 0x4000
	v_lshlrev_b32_e32 v36, 2, v176
	v_and_b32_e32 v56, 12, v36
	v_mbcnt_hi_u32_b32 v36, -1, v190
	v_and_b32_e32 v38, 64, v36
	v_xor_b32_e32 v37, 16, v36
	v_add_u32_e32 v38, 64, v38
	v_cmp_lt_i32_e32 vcc, v37, v38
	v_mul_u32_u24_e32 v182, 0x120, v173
	v_add3_u32 v57, 0, v162, v182
	v_cndmask_b32_e32 v37, v36, v37, vcc
	v_lshlrev_b32_e32 v179, 2, v37
	v_xor_b32_e32 v37, 32, v36
	v_cmp_lt_i32_e32 vcc, v37, v38
	v_readlane_b32 s28, v254, 39
	v_readlane_b32 s29, v254, 40
	v_cndmask_b32_e32 v36, v36, v37, vcc
	v_lshlrev_b32_e32 v180, 2, v36
	v_lshlrev_b32_e32 v163, 2, v177
	v_bfe_u32 v0, v176, 2, 2
	s_mov_b32 s26, s28
	v_readlane_b32 s28, v254, 43
	v_or_b32_e32 v0, v163, v0
	v_readlane_b32 s29, v254, 44
	v_lshlrev_b32_e32 v107, 3, v177
	s_mov_b32 s3, 1
	v_mul_u32_u24_e32 v0, 0x120, v0
	s_waitcnt vmcnt(3)
	ds_write_b128 v34, v[18:21]
	s_waitcnt vmcnt(2)
	ds_write_b128 v35, v[22:25]
	s_waitcnt vmcnt(1)
	ds_write_b128 v34, v[26:29] offset:18432
	s_waitcnt vmcnt(0)
	ds_write_b128 v35, v[30:33] offset:18432
	v_lshl_add_u64 v[26:27], v[58:59], 0, s[34:35]
	v_lshl_add_u64 v[18:19], s[10:11], 0, v[26:27]
	v_lshl_add_u64 v[30:31], v[94:95], 0, s[34:35]
	v_lshl_add_u64 v[18:19], v[18:19], 0, v[60:61]
	v_lshl_add_u64 v[22:23], s[10:11], 0, v[30:31]
	global_load_dwordx4 v[18:21], v[18:19], off
	v_lshl_add_u64 v[22:23], v[22:23], 0, v[96:97]
	v_lshl_add_u64 v[26:27], s[8:9], 0, v[26:27]
	global_load_dwordx4 v[22:25], v[22:23], off
	v_lshl_add_u64 v[26:27], v[26:27], 0, v[60:61]
	v_lshl_add_u64 v[30:31], s[8:9], 0, v[30:31]
	global_load_dwordx4 v[26:29], v[26:27], off
	v_lshl_add_u64 v[30:31], v[30:31], 0, v[96:97]
	global_load_dwordx4 v[30:33], v[30:31], off
	s_mov_b64 s[34:35], 0x8000
	s_waitcnt lgkmcnt(0)
	s_barrier
; #define LAS __attribute__((address_space(3)))
; template <int NMAP, int VD, bool SWA> ...
;     ...
;     for (int i = 0; i < ntiles; ++i) {
;         const int t = ATT_TILE(i);
;         if (i + 1 < ntiles) { ATT_STORE((i + 1) & 1); if (i + 2 < ntiles) ATT_LOAD(ATT_TILE(i + 2)); }
;         const LAS bf16_t* kS = (const LAS bf16_t*)(lds + (i & 1) * BUFB);
;         const LAS bf16_t* vS = (const LAS bf16_t*)(lds + (i & 1) * BUFB + KBYTES);
;         bf16x8 pf[NMAP][2];
;         f32x4 sacc[NMAP][4];
; #pragma unroll
;         for (int mp = 0; mp < NMAP; ++mp) {
;             bf16x8 kf[4][2];
; #pragma unroll
;             for (int kt = 0; kt < 4; ++kt)
; #pragma unroll
;                 for (int ks = 0; ks < 2; ++ks) kf[kt][ks] = *(const LAS bf16x8*)(kS + (16 * kt + fr) * KP + mp * KMS + ks * 32 + fq * 8);
;             __builtin_amdgcn_sched_barrier(0);
; #pragma unroll
;             for (int kt = 0; kt < 4; ++kt) sacc[mp][kt] = __builtin_amdgcn_mfma_f32_16x16x32_bf16(kf[kt][0], qf[mp][0], negm[mp], 0, 0, 0);
; #pragma unroll
;             for (int kt = 0; kt < 4; ++kt) sacc[mp][kt] = __builtin_amdgcn_mfma_f32_16x16x32_bf16(kf[kt][1], qf[mp][1], sacc[mp][kt], 0, 0, 0);
;         }
;         bf16x8 va[4];
;     ...
; #pragma unroll
;         for (int i2 = 0; i2 < 4; ++i2) ATT_LDV(va[i2], i2);
;         if (SWA && t >= 4) {
;             const int dq = qp0 + 16 * w + fr - (64 * (t - 4) + 4 * fq);
; #pragma unroll
;             for (int kt = 0; kt < 4; ++kt)
; #pragma unroll
;                 for (int r = 0; r < 4; ++r) { const int d = dq - 16 * kt - r; if (d > 128 || d < -128) {
; #pragma unroll
;                     for (int mp = 0; mp < NMAP; ++mp) sacc[mp][kt][r] = -INFINITY; } }
;         }
;         float mx[NMAP];
; #pragma unroll
;         for (int mp = 0; mp < NMAP; ++mp) {
;             float v = fmax2(fmax2(sacc[mp][0][0], sacc[mp][0][1]), fmax2(sacc[mp][0][2], sacc[mp][0][3]));
; #pragma unroll
;             for (int kt = 1; kt < 4; ++kt) v = fmax2(v, fmax2(fmax2(sacc[mp][kt][0], sacc[mp][kt][1]), fmax2(sacc[mp][kt][2], sacc[mp][kt][3])));
;             mx[mp] = v;
;         }
; #pragma unroll
;         for (int mp = 0; mp < NMAP; ++mp) mx[mp] = fmax2(mx[mp], __shfl_xor(mx[mp], 16));
; #pragma unroll
;         for (int mp = 0; mp < NMAP; ++mp) mx[mp] = fmax2(mx[mp], __shfl_xor(mx[mp], 32));
; #pragma unroll
;         for (int mp = 0; mp < NMAP; ++mp) {
	s_waitcnt vmcnt(3)
	ds_write_b128 v34, v[18:21] offset:36864
	s_waitcnt vmcnt(2)
	ds_write_b128 v35, v[22:25] offset:36864
	s_waitcnt vmcnt(1)
	ds_write_b128 v34, v[26:29] offset:55296
	s_waitcnt vmcnt(0)
	ds_write_b128 v35, v[30:33] offset:55296
	v_lshl_add_u64 v[18:19], v[58:59], 0, s[34:35]
	v_lshl_add_u64 v[20:21], s[10:11], 0, v[18:19]
	v_lshl_add_u64 v[18:19], s[8:9], 0, v[18:19]
	v_lshl_add_u64 v[20:21], v[20:21], 0, v[60:61]
	v_lshl_add_u64 v[18:19], v[18:19], 0, v[60:61]
	global_load_dwordx4 v[86:89], v[20:21], off
	global_load_dwordx4 v[98:101], v[18:19], off
	v_lshl_add_u64 v[20:21], v[94:95], 0, s[34:35]
	v_lshl_add_u64 v[22:23], s[10:11], 0, v[20:21]
	v_lshl_add_u64 v[18:19], s[8:9], 0, v[20:21]
	v_lshl_add_u64 v[22:23], v[22:23], 0, v[96:97]
	v_lshl_add_u64 v[18:19], v[18:19], 0, v[96:97]
	global_load_dwordx4 v[90:93], v[22:23], off
	global_load_dwordx4 v[102:105], v[18:19], off
	ds_read_b128 v[18:21], v57
	ds_read_b128 v[22:25], v57 offset:64
	ds_read_b128 v[26:29], v57 offset:4608
	ds_read_b128 v[30:33], v57 offset:4672
	ds_read_b128 v[34:37], v57 offset:9216
	ds_read_b128 v[38:41], v57 offset:9280
	ds_read_b128 v[42:45], v57 offset:13824
	ds_read_b128 v[46:49], v57 offset:13888
	s_waitcnt lgkmcnt(7)
	v_mfma_f32_16x16x32_bf16 v[18:21], v[18:21], v[14:17], 0
	s_waitcnt lgkmcnt(5)
	v_mfma_f32_16x16x32_bf16 v[26:29], v[26:29], v[14:17], 0
	s_waitcnt lgkmcnt(3)
	v_mfma_f32_16x16x32_bf16 v[34:37], v[34:37], v[14:17], 0
	s_waitcnt lgkmcnt(1)
	v_mfma_f32_16x16x32_bf16 v[42:45], v[42:45], v[14:17], 0
	v_mfma_f32_16x16x32_bf16 v[18:21], v[22:25], v[10:13], v[18:21]
	v_mfma_f32_16x16x32_bf16 v[24:27], v[30:33], v[10:13], v[26:29]
	v_mfma_f32_16x16x32_bf16 v[28:31], v[38:41], v[10:13], v[34:37]
	s_waitcnt lgkmcnt(0)
	v_mfma_f32_16x16x32_bf16 v[32:35], v[46:49], v[10:13], v[42:45]
	s_nop 0
	ds_read_b128 v[36:39], v57 offset:128
	s_nop 0
	ds_read_b128 v[40:43], v57 offset:192
	ds_read_b128 v[44:47], v57 offset:4736
	ds_read_b128 v[48:51], v57 offset:4800
	ds_read_b128 v[52:55], v57 offset:9344
	ds_read_b128 v[62:65], v57 offset:9408
	ds_read_b128 v[66:69], v57 offset:13952
	ds_read_b128 v[70:73], v57 offset:14016
	v_lshlrev_b32_e32 v181, 1, v56
	v_med3_f32 v23, v18, v19, s27
	v_med3_f32 v56, v20, v21, s27
	s_waitcnt lgkmcnt(7)
	v_mfma_f32_16x16x32_bf16 v[36:39], v[36:39], v[6:9], 0
	v_med3_f32 v23, v23, v56, s27
	v_med3_f32 v56, v24, v25, s27
	v_med3_f32 v57, v26, v27, s27
	v_med3_f32 v56, v56, v57, s27
	s_waitcnt lgkmcnt(5)
	v_mfma_f32_16x16x32_bf16 v[44:47], v[44:47], v[6:9], 0
	v_med3_f32 v23, v23, v56, s27
	v_med3_f32 v56, v28, v29, s27
	v_med3_f32 v57, v30, v31, s27
	v_med3_f32 v56, v56, v57, s27
	v_med3_f32 v23, v23, v56, s27
	v_med3_f32 v56, v32, v33, s27
	v_mfma_f32_16x16x32_bf16 v[36:39], v[40:43], v[2:5], v[36:39]
	v_med3_f32 v40, v34, v35, s27
	v_med3_f32 v40, v56, v40, s27
	v_med3_f32 v23, v23, v40, s27
	s_waitcnt lgkmcnt(3)
	v_mfma_f32_16x16x32_bf16 v[52:55], v[52:55], v[6:9], 0
	v_add3_u32 v22, 0, v0, v181
	v_mad_i64_i32 v[58:59], s[8:9], s14, v192, v[58:59]
	v_mfma_f32_16x16x32_bf16 v[40:43], v[48:51], v[2:5], v[44:47]
	v_lshl_add_u64 v[58:59], v[58:59], 0, v[60:61]
	s_and_b64 s[8:9], s[0:1], exec
	s_cselect_b32 s10, 1, 33
	s_waitcnt lgkmcnt(1)
	v_mfma_f32_16x16x32_bf16 v[66:69], v[66:69], v[6:9], 0
	v_med3_f32 v44, v36, v37, s27
	v_med3_f32 v45, v38, v39, s27
	v_med3_f32 v56, v44, v45, s27
	v_mfma_f32_16x16x32_bf16 v[44:47], v[62:65], v[2:5], v[52:55]
	v_med3_f32 v48, v40, v41, s27
	v_med3_f32 v49, v42, v43, s27
	s_lshl_b32 s11, s10, 14
	v_med3_f32 v52, v48, v49, s27
	s_waitcnt lgkmcnt(0)
	v_mfma_f32_16x16x32_bf16 v[48:51], v[70:73], v[2:5], v[66:69]
	s_nop 1
	v_med3_f32 v53, v44, v45, s27
	v_med3_f32 v54, v46, v47, s27
	v_med3_f32 v52, v56, v52, s27
	v_med3_f32 v53, v53, v54, s27
	v_med3_f32 v52, v52, v53, s27
	s_nop 0
	v_med3_f32 v53, v48, v49, s27
	v_med3_f32 v54, v50, v51, s27
	v_med3_f32 v53, v53, v54, s27
	v_med3_f32 v54, v52, v53, s27
	ds_bpermute_b32 v55, v179, v23
	ds_bpermute_b32 v56, v179, v54
	ds_read_b64_tr_b16 v[52:53], v22 offset:18432
	ds_read_b64_tr_b16 v[62:63], v22 offset:18464
	ds_read_b64_tr_b16 v[66:67], v22 offset:18496
	ds_read_b64_tr_b16 v[70:71], v22 offset:18528
	s_waitcnt lgkmcnt(5)
	v_med3_f32 v23, v23, v55, s27
	s_waitcnt lgkmcnt(4)
	v_med3_f32 v56, v54, v56, s27
	ds_bpermute_b32 v57, v180, v23
	ds_bpermute_b32 v74, v180, v56
	ds_read_b64_tr_b16 v[54:55], v22 offset:23040
	ds_read_b64_tr_b16 v[64:65], v22 offset:23072
	ds_read_b64_tr_b16 v[68:69], v22 offset:23104
	ds_read_b64_tr_b16 v[72:73], v22 offset:23136
	s_waitcnt lgkmcnt(5)
	v_med3_f32 v23, v23, v57, s27
	s_waitcnt lgkmcnt(4)
	v_med3_f32 v109, v56, v74, s27
	v_sub_f32_e32 v35, v35, v23
	v_sub_f32_e32 v34, v34, v23
	v_sub_f32_e32 v33, v33, v23
	v_sub_f32_e32 v32, v32, v23
	v_sub_f32_e32 v31, v31, v23
	v_sub_f32_e32 v30, v30, v23
	v_sub_f32_e32 v29, v29, v23
	v_sub_f32_e32 v28, v28, v23
	v_sub_f32_e32 v27, v27, v23
	v_sub_f32_e32 v26, v26, v23
	v_sub_f32_e32 v25, v25, v23
	v_sub_f32_e32 v24, v24, v23
	v_sub_f32_e32 v21, v21, v23
	v_sub_f32_e32 v20, v20, v23
	v_sub_f32_e32 v19, v19, v23
	v_sub_f32_e32 v18, v18, v23
	v_exp_f32_e32 v111, v28
	v_exp_f32_e32 v156, v29
	v_exp_f32_e32 v157, v30
	v_exp_f32_e32 v164, v31
	v_exp_f32_e32 v165, v32
	v_exp_f32_e32 v166, v33
	v_exp_f32_e32 v167, v34
	v_exp_f32_e32 v183, v35
	v_sub_f32_e32 v28, v43, v109
	v_sub_f32_e32 v29, v42, v109
	v_sub_f32_e32 v30, v41, v109
	v_sub_f32_e32 v31, v40, v109
	v_sub_f32_e32 v32, v39, v109
	v_sub_f32_e32 v33, v38, v109
	v_sub_f32_e32 v34, v37, v109
	v_sub_f32_e32 v35, v36, v109
	v_exp_f32_e32 v56, v18
	v_exp_f32_e32 v57, v19
	v_exp_f32_e32 v74, v20
	v_exp_f32_e32 v75, v21
	v_exp_f32_e32 v76, v24
	v_exp_f32_e32 v106, v25
	v_exp_f32_e32 v108, v26
	v_exp_f32_e32 v110, v27
	v_cvt_pk_bf16_f32 v24, v56, v57
	v_cvt_pk_bf16_f32 v25, v74, v75
	v_cvt_pk_bf16_f32 v26, v76, v106
	v_cvt_pk_bf16_f32 v27, v108, v110
	v_cvt_pk_bf16_f32 v18, v111, v156
	v_cvt_pk_bf16_f32 v19, v157, v164
	v_cvt_pk_bf16_f32 v20, v165, v166
	v_cvt_pk_bf16_f32 v21, v167, v183
	v_sub_f32_e32 v77, v51, v109
	v_sub_f32_e32 v78, v50, v109
	v_sub_f32_e32 v79, v49, v109
	v_exp_f32_e32 v202, v35
	v_exp_f32_e32 v203, v34
	v_exp_f32_e32 v212, v33
	v_exp_f32_e32 v213, v32
	v_exp_f32_e32 v214, v31
	v_exp_f32_e32 v215, v30
	v_exp_f32_e32 v216, v29
	v_exp_f32_e32 v217, v28
	v_cvt_pk_bf16_f32 v28, v202, v203
	s_waitcnt lgkmcnt(3)
; __device__ __forceinline__ unsigned cvt_pk_bf16(float lo, float hi) { unsigned r; asm volatile("v_cvt_pk_bf16_f32 %0, %1, %2" : "=v"(r) : "v"(lo), "v"(hi)); return r; }
; template <int NMAP, int VD, bool SWA> ...
;     ...
;             float ps = 0.f;
; #pragma unroll
;             for (int kt = 0; kt < 4; ++kt)
; #pragma unroll
;                 for (int r = 0; r < 4; ++r) { const float p = __builtin_amdgcn_exp2f(sacc[mp][kt][r]); sacc[mp][kt][r] = p; ps += p; }
;             lsum[mp] += ps;
; #pragma unroll
;             for (int s2 = 0; s2 < 2; ++s2) {
;                 u32x4 pk; pk.x = cvt_pk_bf16(sacc[mp][2 * s2][0], sacc[mp][2 * s2][1]); pk.y = cvt_pk_bf16(sacc[mp][2 * s2][2], sacc[mp][2 * s2][3]);
;                 pk.z = cvt_pk_bf16(sacc[mp][2 * s2 + 1][0], sacc[mp][2 * s2 + 1][1]); pk.w = cvt_pk_bf16(sacc[mp][2 * s2 + 1][2], sacc[mp][2 * s2 + 1][3]);
;                 pf[mp][s2] = __builtin_bit_cast(bf16x8, pk);
;             }
;         }
; #pragma unroll
;         for (int idx = 0; idx < 2 * NET; ++idx) {
;             const int et = idx % NET, s2 = idx / NET;
;             const bf16x8 cur = va[idx & 3];
;             if (idx + 4 < 2 * NET) ATT_LDV(va[idx & 3], idx + 4);
; #pragma unroll
;             for (int mp = 0; mp < NMAP; ++mp) oacc[mp][et] = __builtin_amdgcn_mfma_f32_16x16x32_bf16(cur, pf[mp][s2], oacc[mp][et], 0, 0, 0);
;         }
	v_mfma_f32_16x16x32_bf16 v[32:35], v[52:55], v[24:27], 0
	v_cvt_pk_bf16_f32 v29, v212, v213
	v_cvt_pk_bf16_f32 v30, v214, v215
	v_cvt_pk_bf16_f32 v31, v216, v217
	v_sub_f32_e32 v49, v46, v109
	v_mfma_f32_16x16x32_bf16 v[36:39], v[52:55], v[28:31], 0
	v_sub_f32_e32 v52, v48, v109
	v_sub_f32_e32 v48, v47, v109
	v_sub_f32_e32 v50, v45, v109
	v_sub_f32_e32 v44, v44, v109
	s_waitcnt lgkmcnt(2)
	v_mfma_f32_16x16x32_bf16 v[40:43], v[62:65], v[24:27], 0
	v_exp_f32_e32 v218, v44
	v_exp_f32_e32 v219, v50
	v_exp_f32_e32 v220, v49
	v_mfma_f32_16x16x32_bf16 v[44:47], v[62:65], v[28:31], 0
	v_exp_f32_e32 v221, v48
	v_exp_f32_e32 v222, v52
	v_exp_f32_e32 v223, v79
	v_exp_f32_e32 v224, v78
	v_exp_f32_e32 v225, v77
	v_cvt_pk_bf16_f32 v112, v218, v219
	v_cvt_pk_bf16_f32 v113, v220, v221
	v_cvt_pk_bf16_f32 v114, v222, v223
	v_cvt_pk_bf16_f32 v115, v224, v225
	ds_read_b64_tr_b16 v[64:65], v22 offset:23168
	ds_read_b64_tr_b16 v[62:63], v22 offset:18560
	s_waitcnt lgkmcnt(3)
	v_mfma_f32_16x16x32_bf16 v[48:51], v[66:69], v[24:27], 0
	v_mfma_f32_16x16x32_bf16 v[52:55], v[66:69], v[28:31], 0
	ds_read_b64_tr_b16 v[68:69], v22 offset:23200
	ds_read_b64_tr_b16 v[66:67], v22 offset:18592
	s_waitcnt lgkmcnt(2)
	v_mfma_f32_16x16x32_bf16 v[124:127], v[62:65], v[24:27], 0
	v_mfma_f32_16x16x32_bf16 v[128:131], v[62:65], v[28:31], 0
	ds_read_b64_tr_b16 v[62:63], v22 offset:18624
	ds_read_b64_tr_b16 v[64:65], v22 offset:23232
	s_waitcnt lgkmcnt(2)
	v_mfma_f32_16x16x32_bf16 v[132:135], v[66:69], v[24:27], 0
	v_mfma_f32_16x16x32_bf16 v[136:139], v[66:69], v[28:31], 0
	ds_read_b64_tr_b16 v[66:67], v22 offset:18656
	s_waitcnt lgkmcnt(1)
	v_mfma_f32_16x16x32_bf16 v[140:143], v[62:65], v[24:27], 0
	v_mfma_f32_16x16x32_bf16 v[144:147], v[62:65], v[28:31], 0
	ds_read_b64_tr_b16 v[68:69], v22 offset:23264
	ds_read_b64_tr_b16 v[62:63], v22 offset:27648
	v_mfma_f32_16x16x32_bf16 v[116:119], v[70:73], v[24:27], 0
	s_waitcnt lgkmcnt(1)
	v_mfma_f32_16x16x32_bf16 v[148:151], v[66:69], v[24:27], 0
	ds_read_b64_tr_b16 v[64:65], v22 offset:32256
	ds_read_b64_tr_b16 v[24:25], v22 offset:27680
	ds_read_b64_tr_b16 v[152:153], v22 offset:27712
	s_waitcnt lgkmcnt(2)
	v_mfma_f32_16x16x32_bf16 v[78:81], v[62:65], v[18:21], v[32:35]
	s_nop 2
	v_add_f32_e32 v32, 0, v56
	v_add_f32_e32 v32, v57, v32
	v_add_f32_e32 v32, v74, v32
	v_add_f32_e32 v32, v75, v32
	v_mfma_f32_16x16x32_bf16 v[120:123], v[70:73], v[28:31], 0
	v_add_f32_e32 v32, v76, v32
	v_add_f32_e32 v32, v106, v32
	v_add_f32_e32 v32, v108, v32
	v_mfma_f32_16x16x32_bf16 v[168:171], v[66:69], v[28:31], 0
	ds_read_b64_tr_b16 v[28:29], v22 offset:27744
	ds_read_b64_tr_b16 v[26:27], v22 offset:32288
	ds_read_b64_tr_b16 v[154:155], v22 offset:32320
	ds_read_b64_tr_b16 v[30:31], v22 offset:32352
	v_add_f32_e32 v32, v110, v32
	s_waitcnt lgkmcnt(2)
	v_mfma_f32_16x16x32_bf16 v[74:77], v[24:27], v[18:21], v[40:43]
	v_mfma_f32_16x16x32_bf16 v[70:73], v[24:27], v[112:115], v[44:47]
	v_add_f32_e32 v24, v111, v32
	v_add_f32_e32 v24, v156, v24
	v_add_f32_e32 v24, v157, v24
	v_add_f32_e32 v24, v164, v24
	v_add_f32_e32 v24, v165, v24
	v_add_f32_e32 v24, v166, v24
	v_mfma_f32_16x16x32_bf16 v[82:85], v[62:65], v[112:115], v[36:39]
	s_nop 2
	v_add_f32_e32 v36, v167, v24
	s_waitcnt lgkmcnt(1)
	v_mfma_f32_16x16x32_bf16 v[66:69], v[152:155], v[18:21], v[48:51]
	ds_read_b64_tr_b16 v[24:25], v22 offset:27776
	ds_read_b64_tr_b16 v[26:27], v22 offset:32384
	v_mfma_f32_16x16x32_bf16 v[62:65], v[152:155], v[112:115], v[52:55]
	s_waitcnt lgkmcnt(2)
	v_mfma_f32_16x16x32_bf16 v[54:57], v[28:31], v[18:21], v[116:119]
	ds_read_b64_tr_b16 v[32:33], v22 offset:27808
	s_nop 1
	ds_read_b64_tr_b16 v[116:117], v22 offset:27840
	ds_read_b64_tr_b16 v[152:153], v22 offset:27872
	ds_read_b64_tr_b16 v[34:35], v22 offset:32416
	ds_read_b64_tr_b16 v[118:119], v22 offset:32448
	ds_read_b64_tr_b16 v[154:155], v22 offset:32480
	v_add_f32_e32 v22, v183, v36
	v_pk_add_f32 v[166:167], v[22:23], 0 op_sel_hi:[1,0]
	v_add_f32_e32 v22, 0, v202
	v_add_f32_e32 v22, v203, v22
	v_add_f32_e32 v22, v212, v22
	v_add_f32_e32 v22, v213, v22
	v_add_f32_e32 v22, v214, v22
	v_add_f32_e32 v22, v215, v22
	v_add_f32_e32 v22, v216, v22
	v_add_f32_e32 v22, v217, v22
	v_add_f32_e32 v22, v218, v22
	v_add_f32_e32 v22, v219, v22
	v_add_f32_e32 v22, v220, v22
	v_add_f32_e32 v22, v221, v22
	v_add_f32_e32 v22, v222, v22
	v_add_f32_e32 v22, v223, v22
	v_add_f32_e32 v108, v224, v22
	v_mfma_f32_16x16x32_bf16 v[50:53], v[28:31], v[112:115], v[120:123]
	v_add_f32_e32 v108, v225, v108
	v_pk_add_f32 v[164:165], v[108:109], 0 op_sel_hi:[1,0]
	v_xor_b32_e32 v106, 0x80000000, v167
	s_waitcnt lgkmcnt(6)
	v_mfma_f32_16x16x32_bf16 v[46:49], v[24:27], v[18:21], v[124:127]
	v_xor_b32_e32 v110, 0x80000000, v165
	v_lshlrev_b32_e32 v183, 1, v107
	v_mov_b32_e32 v111, v110
	v_mfma_f32_16x16x32_bf16 v[42:45], v[24:27], v[112:115], v[128:131]
	v_mov_b32_e32 v107, v106
	v_mov_b32_e32 v108, v106
	v_mov_b32_e32 v109, v106
	s_waitcnt lgkmcnt(2)
	v_mfma_f32_16x16x32_bf16 v[38:41], v[32:35], v[18:21], v[132:135]
	s_waitcnt lgkmcnt(0)
	s_barrier
	v_mfma_f32_16x16x32_bf16 v[34:37], v[32:35], v[112:115], v[136:139]
	v_mfma_f32_16x16x32_bf16 v[30:33], v[116:119], v[18:21], v[140:143]
	v_mfma_f32_16x16x32_bf16 v[26:29], v[116:119], v[112:115], v[144:147]
	v_mfma_f32_16x16x32_bf16 v[22:25], v[152:155], v[18:21], v[148:151]
	v_mfma_f32_16x16x32_bf16 v[18:21], v[152:155], v[112:115], v[168:171]
	v_mov_b32_e32 v112, v110
	v_mov_b32_e32 v113, v110
	s_nop 0
	v_lshl_add_u64 v[168:169], s[4:5], 0, v[58:59]
	v_mad_i64_i32 v[58:59], s[8:9], s14, v192, v[94:95]
	v_lshl_add_u64 v[58:59], v[58:59], 0, v[96:97]
	v_lshl_add_u64 v[170:171], s[4:5], 0, v[58:59]
	s_mov_b64 s[8:9], 0
	v_subrev_u32_e32 v236, s4, v168
	v_subrev_u32_e32 v237, s4, v170
	v_add_u32_e32 v238, 0x1200000, v236
	v_add_u32_e32 v239, 0x1200000, v237
	s_add_u32 s34, s4, 0x1810c000
	s_addc_u32 s35, s5, 0
	v_mov_b32_e32 v240, 0x3f803f80
	v_mov_b32_e32 v241, v240
	v_mov_b32_e32 v242, v240
	v_mov_b32_e32 v243, v240
	v_mov_b32_e32 v244, 0
	v_mov_b32_e32 v245, 0
	v_mov_b32_e32 v246, 0
	v_mov_b32_e32 v247, 0
	v_mov_b32_e32 v248, 0
	v_mov_b32_e32 v249, 0
	v_mov_b32_e32 v250, 0
	v_mov_b32_e32 v251, 0
	s_branch .LBB0_125
; __device__ __forceinline__ unsigned cvt_pk_bf16(float lo, float hi) { unsigned r; asm volatile("v_cvt_pk_bf16_f32 %0, %1, %2" : "=v"(r) : "v"(lo), "v"(hi)); return r; }
; __device__ __forceinline__ float fmax2(float a, float b) { return __builtin_amdgcn_fmed3f(a, b, 3.0e38f); }
; template <int NMAP, int VD, bool SWA> ...
;     ...
;         for (int mp = 0; mp < NMAP; ++mp) mx[mp] = fmax2(mx[mp], __shfl_xor(mx[mp], 16));
; #pragma unroll
;         for (int mp = 0; mp < NMAP; ++mp) mx[mp] = fmax2(mx[mp], __shfl_xor(mx[mp], 32));
; #pragma unroll
;         for (int mp = 0; mp < NMAP; ++mp) {
;             if (i == 0 || __builtin_amdgcn_ballot_w64(mx[mp] > 8.0f) != 0ull) {
;                 const float delta = (i == 0) ? mx[mp] : fmaxf(mx[mp], 0.f), alpha = (i == 0) ? 0.f : __builtin_amdgcn_exp2f(-delta);
;                 mrun[mp] += delta; negm[mp] = (f32x4){-mrun[mp], -mrun[mp], -mrun[mp], -mrun[mp]}; lsum[mp] *= alpha;
; #pragma unroll
;                 for (int kt = 0; kt < 4; ++kt) sacc[mp][kt] = sacc[mp][kt] - delta;
; #pragma unroll
;                 for (int et = 0; et < NET; ++et) oacc[mp][et] = oacc[mp][et] * alpha;
;             }
;             float ps = 0.f;
; #pragma unroll
;             for (int kt = 0; kt < 4; ++kt)
; #pragma unroll
;                 for (int r = 0; r < 4; ++r) { const float p = __builtin_amdgcn_exp2f(sacc[mp][kt][r]); sacc[mp][kt][r] = p; ps += p; }
;             lsum[mp] += ps;
; #pragma unroll
;             for (int s2 = 0; s2 < 2; ++s2) {
;                 u32x4 pk; pk.x = cvt_pk_bf16(sacc[mp][2 * s2][0], sacc[mp][2 * s2][1]); pk.y = cvt_pk_bf16(sacc[mp][2 * s2][2], sacc[mp][2 * s2][3]);
;                 pk.z = cvt_pk_bf16(sacc[mp][2 * s2 + 1][0], sacc[mp][2 * s2 + 1][1]); pk.w = cvt_pk_bf16(sacc[mp][2 * s2 + 1][2], sacc[mp][2 * s2 + 1][3]);
;                 pf[mp][s2] = __builtin_bit_cast(bf16x8, pk);
;             }
;         }
; #pragma unroll
;         for (int idx = 0; idx < 2 * NET; ++idx) {
;             const int et = idx % NET, s2 = idx / NET;
;             const bf16x8 cur = va[idx & 3];
;             if (idx + 4 < 2 * NET) ATT_LDV(va[idx & 3], idx + 4);
; #pragma unroll
;             for (int mp = 0; mp < NMAP; ++mp) oacc[mp][et] = __builtin_amdgcn_mfma_f32_16x16x32_bf16(cur, pf[mp][s2], oacc[mp][et], 0, 0, 0);
;         }
.LBB0_123:
	ds_bpermute_b32 v94, v179, v225
	s_waitcnt lgkmcnt(0)
	v_max_f32_e32 v225, v225, v94
	ds_bpermute_b32 v94, v180, v225
	s_waitcnt lgkmcnt(0)
	v_max_f32_e32 v225, v225, v94
	v_max_f32_e32 v94, v225, v225
	v_max_f32_e32 v97, 0, v94
	v_exp_f32_e64 v96, -v97
	v_sub_f32_e32 v142, v142, v97
	v_sub_f32_e32 v143, v143, v97
	v_sub_f32_e32 v144, v144, v97
	v_pk_add_f32 v[94:95], v[164:165], v[96:97]
	v_pk_mul_f32 v[164:165], v[164:165], v[96:97]
	v_xor_b32_e32 v94, 0x80000000, v95
	v_mov_b32_e32 v165, v95
	v_sub_f32_e32 v145, v145, v97
	v_sub_f32_e32 v138, v138, v97
	v_sub_f32_e32 v139, v139, v97
	v_sub_f32_e32 v140, v140, v97
	v_sub_f32_e32 v141, v141, v97
	v_sub_f32_e32 v118, v118, v97
	v_sub_f32_e32 v119, v119, v97
	v_sub_f32_e32 v120, v120, v97
	v_sub_f32_e32 v121, v121, v97
	v_sub_f32_e32 v114, v114, v97
	v_sub_f32_e32 v115, v115, v97
	v_sub_f32_e32 v116, v116, v97
	v_sub_f32_e32 v117, v117, v97
	v_pk_mul_f32 v[84:85], v[84:85], v[96:97] op_sel_hi:[1,0]
	v_pk_mul_f32 v[82:83], v[82:83], v[96:97] op_sel_hi:[1,0]
	v_pk_mul_f32 v[72:73], v[72:73], v[96:97] op_sel_hi:[1,0]
	v_pk_mul_f32 v[70:71], v[70:71], v[96:97] op_sel_hi:[1,0]
	v_pk_mul_f32 v[64:65], v[64:65], v[96:97] op_sel_hi:[1,0]
	v_pk_mul_f32 v[62:63], v[62:63], v[96:97] op_sel_hi:[1,0]
	v_pk_mul_f32 v[52:53], v[52:53], v[96:97] op_sel_hi:[1,0]
	v_pk_mul_f32 v[50:51], v[50:51], v[96:97] op_sel_hi:[1,0]
	v_pk_mul_f32 v[44:45], v[44:45], v[96:97] op_sel_hi:[1,0]
	v_pk_mul_f32 v[42:43], v[42:43], v[96:97] op_sel_hi:[1,0]
	v_pk_mul_f32 v[36:37], v[36:37], v[96:97] op_sel_hi:[1,0]
	v_pk_mul_f32 v[34:35], v[34:35], v[96:97] op_sel_hi:[1,0]
	v_pk_mul_f32 v[28:29], v[28:29], v[96:97] op_sel_hi:[1,0]
	v_pk_mul_f32 v[26:27], v[26:27], v[96:97] op_sel_hi:[1,0]
	v_pk_mul_f32 v[20:21], v[20:21], v[96:97] op_sel_hi:[1,0]
	v_pk_mul_f32 v[18:19], v[18:19], v[96:97] op_sel_hi:[1,0]
	v_pk_mul_f32 v[248:249], v[248:249], v[96:97] op_sel_hi:[1,0]
	v_pk_mul_f32 v[250:251], v[250:251], v[96:97] op_sel_hi:[1,0]
	v_mov_b32_e32 v95, v94
	v_mov_b32_e32 v96, v94
	v_mov_b32_e32 v97, v94
	v_mov_b32_e32 v110, v94
	v_mov_b32_e32 v111, v94
	v_mov_b32_e32 v112, v94
	v_mov_b32_e32 v113, v94
.LBB0_124:
	v_exp_f32_e32 v142, v142
	v_exp_f32_e32 v143, v143
	v_exp_f32_e32 v144, v144
	v_exp_f32_e32 v145, v145
	v_exp_f32_e32 v202, v138
	v_exp_f32_e32 v203, v139
	v_exp_f32_e32 v225, v140
	v_exp_f32_e32 v226, v141
	v_cvt_pk_bf16_f32 v138, v142, v143
	v_cvt_pk_bf16_f32 v139, v144, v145
	v_cvt_pk_bf16_f32 v140, v202, v203
	v_cvt_pk_bf16_f32 v141, v225, v226
	v_exp_f32_e32 v227, v118
	v_exp_f32_e32 v228, v119
	v_exp_f32_e32 v229, v120
	v_exp_f32_e32 v230, v121
	v_exp_f32_e32 v231, v114
	v_exp_f32_e32 v232, v115
	v_exp_f32_e32 v233, v116
	v_exp_f32_e32 v234, v117
	v_cvt_pk_bf16_f32 v114, v227, v228
	v_cvt_pk_bf16_f32 v115, v229, v230
	v_cvt_pk_bf16_f32 v116, v231, v232
	v_cvt_pk_bf16_f32 v117, v233, v234
	v_mfma_f32_16x16x32_bf16 v[244:247], v[240:243], v[150:153], v[244:247]
	v_mfma_f32_16x16x32_bf16 v[248:251], v[240:243], v[138:141], v[248:251]
	v_mfma_f32_16x16x32_bf16 v[244:247], v[240:243], v[146:149], v[244:247]
	v_mfma_f32_16x16x32_bf16 v[248:251], v[240:243], v[114:117], v[248:251]
	ds_read_b64_tr_b16 v[120:121], v212 offset:23168
	ds_read_b64_tr_b16 v[118:119], v212 offset:18560
	v_mfma_f32_16x16x32_bf16 v[54:57], v[122:125], v[150:153], v[54:57]
	s_add_u32 s8, s8, 0x4000
	s_cmp_lg_u32 s11, s8
	v_mfma_f32_16x16x32_bf16 v[50:53], v[122:125], v[138:141], v[50:53]
	ds_read_b64_tr_b16 v[122:123], v212 offset:18592
	ds_read_b64_tr_b16 v[124:125], v212 offset:23200
	s_waitcnt lgkmcnt(2)
	v_mfma_f32_16x16x32_bf16 v[46:49], v[118:121], v[150:153], v[46:49]
	v_mfma_f32_16x16x32_bf16 v[42:45], v[118:121], v[138:141], v[42:45]
	ds_read_b64_tr_b16 v[118:119], v212 offset:18624
	s_waitcnt lgkmcnt(1)
	v_mfma_f32_16x16x32_bf16 v[38:41], v[122:125], v[150:153], v[38:41]
	v_mfma_f32_16x16x32_bf16 v[34:37], v[122:125], v[138:141], v[34:37]
	ds_read_b64_tr_b16 v[120:121], v212 offset:23232
	ds_read_b64_tr_b16 v[122:123], v212 offset:18656
	ds_read_b64_tr_b16 v[124:125], v212 offset:23264
	v_mfma_f32_16x16x32_bf16 v[66:69], v[126:129], v[150:153], v[66:69]
	v_mfma_f32_16x16x32_bf16 v[62:65], v[126:129], v[138:141], v[62:65]
	s_waitcnt lgkmcnt(2)
	v_mfma_f32_16x16x32_bf16 v[30:33], v[118:121], v[150:153], v[30:33]
	v_mfma_f32_16x16x32_bf16 v[26:29], v[118:121], v[138:141], v[26:29]
	ds_read_b64_tr_b16 v[118:119], v212 offset:27648
	ds_read_b64_tr_b16 v[120:121], v212 offset:32256
	v_mfma_f32_16x16x32_bf16 v[78:81], v[134:137], v[150:153], v[78:81]
	v_mfma_f32_16x16x32_bf16 v[82:85], v[134:137], v[138:141], v[82:85]
	s_waitcnt lgkmcnt(2)
	v_mfma_f32_16x16x32_bf16 v[22:25], v[122:125], v[150:153], v[22:25]
	v_mfma_f32_16x16x32_bf16 v[18:21], v[122:125], v[138:141], v[18:21]
	s_waitcnt lgkmcnt(0)
	v_mfma_f32_16x16x32_bf16 v[78:81], v[118:121], v[146:149], v[78:81]
	v_mfma_f32_16x16x32_bf16 v[82:85], v[118:121], v[114:117], v[82:85]
	v_mfma_f32_16x16x32_bf16 v[74:77], v[130:133], v[150:153], v[74:77]
	v_mfma_f32_16x16x32_bf16 v[70:73], v[130:133], v[138:141], v[70:73]
	ds_read_b64_tr_b16 v[126:127], v212 offset:27680
	ds_read_b64_tr_b16 v[130:131], v212 offset:27712
	ds_read_b64_tr_b16 v[134:135], v212 offset:27744
	ds_read_b64_tr_b16 v[128:129], v212 offset:32288
	ds_read_b64_tr_b16 v[132:133], v212 offset:32320
	ds_read_b64_tr_b16 v[136:137], v212 offset:32352
	ds_read_b64_tr_b16 v[118:119], v212 offset:27776
	ds_read_b64_tr_b16 v[120:121], v212 offset:32384
	s_waitcnt lgkmcnt(2)
	v_mfma_f32_16x16x32_bf16 v[54:57], v[134:137], v[146:149], v[54:57]
	v_mfma_f32_16x16x32_bf16 v[50:53], v[134:137], v[114:117], v[50:53]
	s_waitcnt lgkmcnt(0)
	v_mfma_f32_16x16x32_bf16 v[46:49], v[118:121], v[146:149], v[46:49]
	v_mfma_f32_16x16x32_bf16 v[42:45], v[118:121], v[114:117], v[42:45]
	v_mfma_f32_16x16x32_bf16 v[74:77], v[126:129], v[146:149], v[74:77]
	v_mfma_f32_16x16x32_bf16 v[70:73], v[126:129], v[114:117], v[70:73]
	v_mfma_f32_16x16x32_bf16 v[66:69], v[130:133], v[146:149], v[66:69]
	v_mfma_f32_16x16x32_bf16 v[62:65], v[130:133], v[114:117], v[62:65]
	ds_read_b64_tr_b16 v[122:123], v212 offset:27808
	ds_read_b64_tr_b16 v[126:127], v212 offset:27840
	ds_read_b64_tr_b16 v[130:131], v212 offset:27872
	ds_read_b64_tr_b16 v[124:125], v212 offset:32416
	ds_read_b64_tr_b16 v[128:129], v212 offset:32448
	ds_read_b64_tr_b16 v[132:133], v212 offset:32480
	s_waitcnt lgkmcnt(0)
	v_mfma_f32_16x16x32_bf16 v[38:41], v[122:125], v[146:149], v[38:41]
	s_barrier
	v_mfma_f32_16x16x32_bf16 v[34:37], v[122:125], v[114:117], v[34:37]
	v_mfma_f32_16x16x32_bf16 v[30:33], v[126:129], v[146:149], v[30:33]
	v_mfma_f32_16x16x32_bf16 v[26:29], v[126:129], v[114:117], v[26:29]
	v_mfma_f32_16x16x32_bf16 v[22:25], v[130:133], v[146:149], v[22:25]
	v_mfma_f32_16x16x32_bf16 v[18:21], v[130:133], v[114:117], v[18:21]
	s_cbranch_scc0 .LBB0_130
; #define LAS __attribute__((address_space(3)))
; template <int NMAP, int VD, bool SWA> ...
;     ...
;     for (int i = 0; i < ntiles; ++i) {
;         const int t = ATT_TILE(i);
;         if (i + 1 < ntiles) { ATT_STORE((i + 1) & 1); if (i + 2 < ntiles) ATT_LOAD(ATT_TILE(i + 2)); }
;         const LAS bf16_t* kS = (const LAS bf16_t*)(lds + (i & 1) * BUFB);
;         const LAS bf16_t* vS = (const LAS bf16_t*)(lds + (i & 1) * BUFB + KBYTES);
;         bf16x8 pf[NMAP][2];
;         f32x4 sacc[NMAP][4];
; #pragma unroll
;         for (int mp = 0; mp < NMAP; ++mp) {
;             bf16x8 kf[4][2];
; #pragma unroll
;             for (int kt = 0; kt < 4; ++kt)
; #pragma unroll
;                 for (int ks = 0; ks < 2; ++ks) kf[kt][ks] = *(const LAS bf16x8*)(kS + (16 * kt + fr) * KP + mp * KMS + ks * 32 + fq * 8);
;             __builtin_amdgcn_sched_barrier(0);
; #pragma unroll
;             for (int kt = 0; kt < 4; ++kt) sacc[mp][kt] = __builtin_amdgcn_mfma_f32_16x16x32_bf16(kf[kt][0], qf[mp][0], negm[mp], 0, 0, 0);
; #pragma unroll
;             for (int kt = 0; kt < 4; ++kt) sacc[mp][kt] = __builtin_amdgcn_mfma_f32_16x16x32_bf16(kf[kt][1], qf[mp][1], sacc[mp][kt], 0, 0, 0);
;         }
;         bf16x8 va[4];
;     ...
; #pragma unroll
;         for (int i2 = 0; i2 < 4; ++i2) ATT_LDV(va[i2], i2);
;         if (SWA && t >= 4) {
;             const int dq = qp0 + 16 * w + fr - (64 * (t - 4) + 4 * fq);
; #pragma unroll
;             for (int kt = 0; kt < 4; ++kt)
; #pragma unroll
;                 for (int r = 0; r < 4; ++r) { const int d = dq - 16 * kt - r; if (d > 128 || d < -128) {
; #pragma unroll
;                     for (int mp = 0; mp < NMAP; ++mp) sacc[mp][kt][r] = -INFINITY; } }
;         }
;         float mx[NMAP];
; #pragma unroll
;         for (int mp = 0; mp < NMAP; ++mp) {
;             float v = fmax2(fmax2(sacc[mp][0][0], sacc[mp][0][1]), fmax2(sacc[mp][0][2], sacc[mp][0][3]));
; #pragma unroll
;             for (int kt = 1; kt < 4; ++kt) v = fmax2(v, fmax2(fmax2(sacc[mp][kt][0], sacc[mp][kt][1]), fmax2(sacc[mp][kt][2], sacc[mp][kt][3])));
;             mx[mp] = v;
;         }
; #pragma unroll
;         for (int mp = 0; mp < NMAP; ++mp) mx[mp] = fmax2(mx[mp], __shfl_xor(mx[mp], 16));
; #pragma unroll
;         for (int mp = 0; mp < NMAP; ++mp) mx[mp] = fmax2(mx[mp], __shfl_xor(mx[mp], 32));
; #pragma unroll
;         for (int mp = 0; mp < NMAP; ++mp) {
.LBB0_125:
	s_mov_b32 s15, s3
	s_add_i32 s3, s3, 1
	s_bitcmp1_b32 s3, 0
	s_cselect_b32 s14, 0x9000, 0
	v_add3_u32 v58, s14, v208, v209
	v_add3_u32 v59, s14, v210, v211
	s_waitcnt vmcnt(0)
	ds_write_b128 v58, v[86:89]
	ds_write_b128 v59, v[90:93]
	ds_write_b128 v58, v[98:101] offset:18432
	ds_write_b128 v59, v[102:105] offset:18432
	global_load_dwordx4 v[86:89], v236, s[34:35]
	global_load_dwordx4 v[90:93], v237, s[34:35]
	global_load_dwordx4 v[98:101], v238, s[34:35]
	global_load_dwordx4 v[102:105], v239, s[34:35]
	s_add_u32 s34, s34, 0x4000
	s_addc_u32 s35, s35, 0
	s_bitcmp1_b32 s15, 0
	s_cselect_b32 s15, 0x9000, 0
	v_add3_u32 v138, s15, v183, v182
	ds_read_b128 v[58:61], v138
	ds_read_b128 v[94:97], v138 offset:64
	ds_read_b128 v[114:117], v138 offset:4608
	ds_read_b128 v[118:121], v138 offset:4672
	ds_read_b128 v[122:125], v138 offset:9216
	ds_read_b128 v[126:129], v138 offset:9280
	ds_read_b128 v[130:133], v138 offset:13824
	ds_read_b128 v[134:137], v138 offset:13888
	s_waitcnt lgkmcnt(1)
	v_mfma_f32_16x16x32_bf16 v[58:61], v[58:61], v[14:17], v[106:109]
	v_mfma_f32_16x16x32_bf16 v[114:117], v[114:117], v[14:17], v[106:109]
	v_mfma_f32_16x16x32_bf16 v[122:125], v[122:125], v[14:17], v[106:109]
	v_mfma_f32_16x16x32_bf16 v[130:133], v[130:133], v[14:17], v[106:109]
	v_mfma_f32_16x16x32_bf16 v[154:157], v[94:97], v[10:13], v[58:61]
	v_mfma_f32_16x16x32_bf16 v[150:153], v[118:121], v[10:13], v[114:117]
	v_mfma_f32_16x16x32_bf16 v[146:149], v[126:129], v[10:13], v[122:125]
	s_waitcnt lgkmcnt(0)
	v_mfma_f32_16x16x32_bf16 v[94:97], v[134:137], v[10:13], v[130:133]
	ds_read_b128 v[58:61], v138 offset:128
	ds_read_b128 v[114:117], v138 offset:192
	ds_read_b128 v[118:121], v138 offset:4736
	ds_read_b128 v[122:125], v138 offset:4800
	ds_read_b128 v[126:129], v138 offset:9344
	ds_read_b128 v[130:133], v138 offset:9408
	ds_read_b128 v[134:137], v138 offset:13952
	ds_read_b128 v[212:215], v138 offset:14016
	s_waitcnt lgkmcnt(1)
	v_mfma_f32_16x16x32_bf16 v[58:61], v[58:61], v[6:9], v[110:113]
	v_mfma_f32_16x16x32_bf16 v[118:121], v[118:121], v[6:9], v[110:113]
	v_mfma_f32_16x16x32_bf16 v[142:145], v[114:117], v[2:5], v[58:61]
	v_max3_f32 v235, v154, v155, v156
	v_max3_f32 v235, v235, v157, v150
	v_max3_f32 v235, v235, v151, v152
	v_mfma_f32_16x16x32_bf16 v[126:129], v[126:129], v[6:9], v[110:113]
	v_max3_f32 v235, v235, v153, v146
	v_max3_f32 v235, v235, v147, v148
	v_mfma_f32_16x16x32_bf16 v[134:137], v[134:137], v[6:9], v[110:113]
	v_max3_f32 v235, v235, v149, v94
	v_max3_f32 v235, v235, v95, v96
	v_mfma_f32_16x16x32_bf16 v[138:141], v[122:125], v[2:5], v[118:121]
	v_max_f32_e32 v235, v235, v97
	v_mfma_f32_16x16x32_bf16 v[118:121], v[130:133], v[2:5], v[126:129]
	v_max3_f32 v59, v142, v143, v144
	s_waitcnt lgkmcnt(0)
	v_mfma_f32_16x16x32_bf16 v[114:117], v[212:215], v[2:5], v[134:137]
	v_add3_u32 v212, s15, v0, v181
	ds_read_b64_tr_b16 v[134:135], v212 offset:18432
	ds_read_b64_tr_b16 v[130:131], v212 offset:18464
	ds_read_b64_tr_b16 v[136:137], v212 offset:23040
	ds_read_b64_tr_b16 v[132:133], v212 offset:23072
	ds_read_b64_tr_b16 v[126:127], v212 offset:18496
	ds_read_b64_tr_b16 v[128:129], v212 offset:23104
	ds_read_b64_tr_b16 v[122:123], v212 offset:18528
	ds_read_b64_tr_b16 v[124:125], v212 offset:23136
	v_max3_f32 v59, v59, v145, v138
	v_max3_f32 v59, v59, v139, v140
	v_max3_f32 v59, v59, v141, v118
	v_max3_f32 v59, v59, v119, v120
	v_max3_f32 v59, v59, v121, v114
	v_max3_f32 v59, v59, v115, v116
	v_max_f32_e32 v225, v59, v117
	v_cmp_lt_f32_e32 vcc, s72, v235
	s_cbranch_vccz .LBB0_127
	ds_bpermute_b32 v60, v179, v235
	s_waitcnt lgkmcnt(0)
	v_max_f32_e32 v58, v235, v60
	ds_bpermute_b32 v60, v180, v58
	s_waitcnt lgkmcnt(0)
	v_max_f32_e32 v58, v58, v60
	v_max_f32_e32 v58, v58, v58
	v_max_f32_e32 v61, 0, v58
	v_exp_f32_e64 v60, -v61
	v_sub_f32_e32 v154, v154, v61
	v_sub_f32_e32 v155, v155, v61
	v_sub_f32_e32 v156, v156, v61
	v_pk_add_f32 v[58:59], v[166:167], v[60:61]
	v_pk_mul_f32 v[166:167], v[166:167], v[60:61]
	v_xor_b32_e32 v58, 0x80000000, v59
	v_mov_b32_e32 v167, v59
	v_sub_f32_e32 v157, v157, v61
	v_sub_f32_e32 v150, v150, v61
	v_sub_f32_e32 v151, v151, v61
	v_sub_f32_e32 v152, v152, v61
	v_sub_f32_e32 v153, v153, v61
	v_sub_f32_e32 v146, v146, v61
	v_sub_f32_e32 v147, v147, v61
	v_sub_f32_e32 v148, v148, v61
	v_sub_f32_e32 v149, v149, v61
	v_sub_f32_e32 v94, v94, v61
	v_sub_f32_e32 v95, v95, v61
	v_sub_f32_e32 v96, v96, v61
	v_sub_f32_e32 v97, v97, v61
	v_pk_mul_f32 v[80:81], v[80:81], v[60:61] op_sel_hi:[1,0]
	v_pk_mul_f32 v[78:79], v[78:79], v[60:61] op_sel_hi:[1,0]
	v_pk_mul_f32 v[76:77], v[76:77], v[60:61] op_sel_hi:[1,0]
	v_pk_mul_f32 v[74:75], v[74:75], v[60:61] op_sel_hi:[1,0]
	v_pk_mul_f32 v[68:69], v[68:69], v[60:61] op_sel_hi:[1,0]
	v_pk_mul_f32 v[66:67], v[66:67], v[60:61] op_sel_hi:[1,0]
	v_pk_mul_f32 v[56:57], v[56:57], v[60:61] op_sel_hi:[1,0]
	v_pk_mul_f32 v[54:55], v[54:55], v[60:61] op_sel_hi:[1,0]
	v_pk_mul_f32 v[48:49], v[48:49], v[60:61] op_sel_hi:[1,0]
	v_pk_mul_f32 v[46:47], v[46:47], v[60:61] op_sel_hi:[1,0]
	v_pk_mul_f32 v[40:41], v[40:41], v[60:61] op_sel_hi:[1,0]
	v_pk_mul_f32 v[38:39], v[38:39], v[60:61] op_sel_hi:[1,0]
	v_pk_mul_f32 v[32:33], v[32:33], v[60:61] op_sel_hi:[1,0]
	v_pk_mul_f32 v[30:31], v[30:31], v[60:61] op_sel_hi:[1,0]
	v_pk_mul_f32 v[24:25], v[24:25], v[60:61] op_sel_hi:[1,0]
	v_pk_mul_f32 v[22:23], v[22:23], v[60:61] op_sel_hi:[1,0]
	v_pk_mul_f32 v[244:245], v[244:245], v[60:61] op_sel_hi:[1,0]
	v_pk_mul_f32 v[246:247], v[246:247], v[60:61] op_sel_hi:[1,0]
	v_mov_b32_e32 v59, v58
	v_mov_b32_e32 v60, v58
	v_mov_b32_e32 v61, v58
	v_mov_b32_e32 v106, v58
	v_mov_b32_e32 v107, v58
	v_mov_b32_e32 v108, v58
	v_mov_b32_e32 v109, v58
	s_branch .LBB0_128

; #define LAS __attribute__((address_space(3)))
; template <int NMAP, int VD, bool SWA> ...
;     ...
;     for (int i = 0; i < ntiles; ++i) {
;         const int t = ATT_TILE(i);
;         if (i + 1 < ntiles) { ATT_STORE((i + 1) & 1); if (i + 2 < ntiles) ATT_LOAD(ATT_TILE(i + 2)); }
;         const LAS bf16_t* kS = (const LAS bf16_t*)(lds + (i & 1) * BUFB);
;         const LAS bf16_t* vS = (const LAS bf16_t*)(lds + (i & 1) * BUFB + KBYTES);
;         bf16x8 pf[NMAP][2];
;         f32x4 sacc[NMAP][4];
; #pragma unroll
;         for (int mp = 0; mp < NMAP; ++mp) {
;             bf16x8 kf[4][2];
; #pragma unroll
;             for (int kt = 0; kt < 4; ++kt)
; #pragma unroll
;                 for (int ks = 0; ks < 2; ++ks) kf[kt][ks] = *(const LAS bf16x8*)(kS + (16 * kt + fr) * KP + mp * KMS + ks * 32 + fq * 8);
;             __builtin_amdgcn_sched_barrier(0);
; #pragma unroll
;             for (int kt = 0; kt < 4; ++kt) sacc[mp][kt] = __builtin_amdgcn_mfma_f32_16x16x32_bf16(kf[kt][0], qf[mp][0], negm[mp], 0, 0, 0);
; #pragma unroll
;             for (int kt = 0; kt < 4; ++kt) sacc[mp][kt] = __builtin_amdgcn_mfma_f32_16x16x32_bf16(kf[kt][1], qf[mp][1], sacc[mp][kt], 0, 0, 0);
;         }
;         bf16x8 va[4];
;     ...
; #pragma unroll
;         for (int i2 = 0; i2 < 4; ++i2) ATT_LDV(va[i2], i2);
;         if (SWA && t >= 4) {
;             const int dq = qp0 + 16 * w + fr - (64 * (t - 4) + 4 * fq);
; #pragma unroll
;             for (int kt = 0; kt < 4; ++kt)
; #pragma unroll
;                 for (int r = 0; r < 4; ++r) { const int d = dq - 16 * kt - r; if (d > 128 || d < -128) {
; #pragma unroll
;                     for (int mp = 0; mp < NMAP; ++mp) sacc[mp][kt][r] = -INFINITY; } }
;         }
;         float mx[NMAP];
; #pragma unroll
;         for (int mp = 0; mp < NMAP; ++mp) {
;             float v = fmax2(fmax2(sacc[mp][0][0], sacc[mp][0][1]), fmax2(sacc[mp][0][2], sacc[mp][0][3]));
; #pragma unroll
;             for (int kt = 1; kt < 4; ++kt) v = fmax2(v, fmax2(fmax2(sacc[mp][kt][0], sacc[mp][kt][1]), fmax2(sacc[mp][kt][2], sacc[mp][kt][3])));
;             mx[mp] = v;
;         }
; #pragma unroll
;         for (int mp = 0; mp < NMAP; ++mp) mx[mp] = fmax2(mx[mp], __shfl_xor(mx[mp], 16));
; #pragma unroll
;         for (int mp = 0; mp < NMAP; ++mp) mx[mp] = fmax2(mx[mp], __shfl_xor(mx[mp], 32));
; #pragma unroll
;         for (int mp = 0; mp < NMAP; ++mp) {
.LBB0_130:
	v_mov_b64_e32 v[58:59], v[106:107]
	v_mov_b64_e32 v[60:61], v[108:109]
	v_mov_b64_e32 v[94:95], v[110:111]
	v_mov_b64_e32 v[96:97], v[112:113]
	v_fmac_f32_e32 v166, 0x3e800000, v244
	v_fmac_f32_e32 v164, 0x3e800000, v248
	s_bitcmp1_b32 s10, 0
	s_cselect_b32 s3, 0x9000, 0
	s_add_i32 s3, s3, 0
	v_add3_u32 v106, s3, v208, v209
	s_waitcnt vmcnt(3)
	ds_write_b128 v106, v[86:89]
	v_add3_u32 v86, s3, v210, v211
	s_waitcnt vmcnt(2)
	ds_write_b128 v86, v[90:93]
	s_waitcnt vmcnt(1)
	ds_write_b128 v106, v[98:101] offset:18432
	s_waitcnt vmcnt(0)
	ds_write_b128 v86, v[102:105] offset:18432
	v_add3_u32 v122, s14, v183, v182
	ds_read_b128 v[86:89], v122
	ds_read_b128 v[90:93], v122 offset:64
	ds_read_b128 v[98:101], v122 offset:4608
	ds_read_b128 v[102:105], v122 offset:4672
	ds_read_b128 v[106:109], v122 offset:9216
	ds_read_b128 v[110:113], v122 offset:9280
	ds_read_b128 v[114:117], v122 offset:13824
	ds_read_b128 v[118:121], v122 offset:13888
	s_waitcnt lgkmcnt(7)
	v_mfma_f32_16x16x32_bf16 v[86:89], v[86:89], v[14:17], v[58:61]
	s_waitcnt lgkmcnt(5)
	v_mfma_f32_16x16x32_bf16 v[98:101], v[98:101], v[14:17], v[58:61]
	s_waitcnt lgkmcnt(3)
	v_mfma_f32_16x16x32_bf16 v[106:109], v[106:109], v[14:17], v[58:61]
	s_waitcnt lgkmcnt(1)
	v_mfma_f32_16x16x32_bf16 v[114:117], v[114:117], v[14:17], v[58:61]
	v_mfma_f32_16x16x32_bf16 v[134:137], v[90:93], v[10:13], v[86:89]
	v_mfma_f32_16x16x32_bf16 v[130:133], v[102:105], v[10:13], v[98:101]
	v_mfma_f32_16x16x32_bf16 v[126:129], v[110:113], v[10:13], v[106:109]
	s_waitcnt lgkmcnt(0)
	v_mfma_f32_16x16x32_bf16 v[106:109], v[118:121], v[10:13], v[114:117]
	ds_read_b128 v[86:89], v122 offset:128
	ds_read_b128 v[90:93], v122 offset:192
	ds_read_b128 v[98:101], v122 offset:4736
	ds_read_b128 v[102:105], v122 offset:4800
	ds_read_b128 v[110:113], v122 offset:9344
	ds_read_b128 v[114:117], v122 offset:9408
	ds_read_b128 v[118:121], v122 offset:13952
	ds_read_b128 v[138:141], v122 offset:14016
	s_waitcnt lgkmcnt(3)
	v_mfma_f32_16x16x32_bf16 v[110:113], v[110:113], v[6:9], v[94:97]
	s_waitcnt lgkmcnt(1)
	v_mfma_f32_16x16x32_bf16 v[142:145], v[118:121], v[6:9], v[94:97]
	v_mfma_f32_16x16x32_bf16 v[86:89], v[86:89], v[6:9], v[94:97]
	v_mfma_f32_16x16x32_bf16 v[98:101], v[98:101], v[6:9], v[94:97]
	v_mfma_f32_16x16x32_bf16 v[114:117], v[114:117], v[2:5], v[110:113]
	s_waitcnt lgkmcnt(0)
	v_mfma_f32_16x16x32_bf16 v[110:113], v[138:141], v[2:5], v[142:145]
	v_med3_f32 v139, v134, v135, s27
	v_med3_f32 v140, v136, v137, s27
	v_med3_f32 v139, v139, v140, s27
	v_med3_f32 v140, v130, v131, s27
	v_med3_f32 v141, v132, v133, s27
	v_med3_f32 v140, v140, v141, s27
	v_mfma_f32_16x16x32_bf16 v[122:125], v[90:93], v[2:5], v[86:89]
	v_med3_f32 v139, v139, v140, s27
	v_med3_f32 v140, v126, v127, s27
	v_med3_f32 v141, v128, v129, s27
	v_mfma_f32_16x16x32_bf16 v[118:121], v[102:105], v[2:5], v[98:101]
	v_med3_f32 v140, v140, v141, s27
	v_med3_f32 v139, v139, v140, s27
	v_med3_f32 v140, v106, v107, s27
	v_med3_f32 v141, v108, v109, s27
	v_med3_f32 v140, v140, v141, s27
	v_med3_f32 v139, v139, v140, s27
	v_med3_f32 v140, v122, v123, s27
	v_med3_f32 v141, v124, v125, s27
	v_med3_f32 v140, v140, v141, s27
	v_med3_f32 v141, v118, v119, s27
	v_med3_f32 v142, v120, v121, s27
	v_med3_f32 v141, v141, v142, s27
	v_med3_f32 v140, v140, v141, s27
	v_med3_f32 v141, v114, v115, s27
	v_med3_f32 v142, v116, v117, s27
	v_med3_f32 v141, v141, v142, s27
	v_med3_f32 v140, v140, v141, s27
	v_med3_f32 v141, v110, v111, s27
	v_med3_f32 v142, v112, v113, s27
	v_med3_f32 v141, v141, v142, s27
	v_med3_f32 v140, v140, v141, s27
	ds_bpermute_b32 v141, v179, v139
	v_add3_u32 v138, s14, v0, v181
	ds_read_b64_tr_b16 v[102:103], v138 offset:18432
	ds_read_b64_tr_b16 v[98:99], v138 offset:18464
	ds_read_b64_tr_b16 v[104:105], v138 offset:23040
	ds_read_b64_tr_b16 v[100:101], v138 offset:23072
	ds_read_b64_tr_b16 v[90:91], v138 offset:18496
	ds_read_b64_tr_b16 v[92:93], v138 offset:23104
	ds_read_b64_tr_b16 v[86:87], v138 offset:18528
	ds_read_b64_tr_b16 v[88:89], v138 offset:23136
	s_waitcnt lgkmcnt(8)
	v_med3_f32 v141, v139, v141, s27
	ds_bpermute_b32 v139, v179, v140
	s_waitcnt lgkmcnt(0)
	v_med3_f32 v139, v140, v139, s27
	ds_bpermute_b32 v140, v180, v141
	s_waitcnt lgkmcnt(0)
	v_med3_f32 v141, v141, v140, s27
	ds_bpermute_b32 v140, v180, v139
	v_cmp_lt_f32_e32 vcc, s72, v141
	s_cbranch_vccz .LBB0_132
	v_max_f32_e32 v58, v141, v141
	v_max_f32_e32 v59, 0, v58
	v_exp_f32_e64 v60, -v59
	v_add_f32_e32 v58, v167, v59
	v_xor_b32_e32 v58, 0x80000000, v58
	v_sub_f32_e32 v134, v134, v59
	v_mul_f32_e32 v166, v166, v60
	v_sub_f32_e32 v135, v135, v59
	v_sub_f32_e32 v136, v136, v59
	v_sub_f32_e32 v137, v137, v59
	v_sub_f32_e32 v130, v130, v59
	v_sub_f32_e32 v131, v131, v59
	v_sub_f32_e32 v132, v132, v59
	v_sub_f32_e32 v133, v133, v59
	v_sub_f32_e32 v126, v126, v59
	v_sub_f32_e32 v127, v127, v59
	v_sub_f32_e32 v128, v128, v59
	v_sub_f32_e32 v129, v129, v59
	v_sub_f32_e32 v106, v106, v59
	v_sub_f32_e32 v107, v107, v59
	v_sub_f32_e32 v108, v108, v59
	v_sub_f32_e32 v109, v109, v59
	v_pk_mul_f32 v[80:81], v[80:81], v[60:61] op_sel_hi:[1,0]
	v_pk_mul_f32 v[78:79], v[78:79], v[60:61] op_sel_hi:[1,0]
	v_pk_mul_f32 v[76:77], v[76:77], v[60:61] op_sel_hi:[1,0]
	v_pk_mul_f32 v[74:75], v[74:75], v[60:61] op_sel_hi:[1,0]
	v_pk_mul_f32 v[68:69], v[68:69], v[60:61] op_sel_hi:[1,0]
	v_pk_mul_f32 v[66:67], v[66:67], v[60:61] op_sel_hi:[1,0]
	v_pk_mul_f32 v[56:57], v[56:57], v[60:61] op_sel_hi:[1,0]
	v_pk_mul_f32 v[54:55], v[54:55], v[60:61] op_sel_hi:[1,0]
	v_pk_mul_f32 v[48:49], v[48:49], v[60:61] op_sel_hi:[1,0]
	v_pk_mul_f32 v[46:47], v[46:47], v[60:61] op_sel_hi:[1,0]
	v_pk_mul_f32 v[40:41], v[40:41], v[60:61] op_sel_hi:[1,0]
	v_pk_mul_f32 v[38:39], v[38:39], v[60:61] op_sel_hi:[1,0]
	v_pk_mul_f32 v[32:33], v[32:33], v[60:61] op_sel_hi:[1,0]
	v_pk_mul_f32 v[30:31], v[30:31], v[60:61] op_sel_hi:[1,0]
	v_pk_mul_f32 v[24:25], v[24:25], v[60:61] op_sel_hi:[1,0]
	v_pk_mul_f32 v[22:23], v[22:23], v[60:61] op_sel_hi:[1,0]
	v_mov_b32_e32 v59, v58
	v_mov_b32_e32 v60, v58
	v_mov_b32_e32 v61, v58
